# P2 item-end barrier: dropped the vmcnt(0) drain (only lgkmcnt needed; GEMM items drain explicitly)
# speedup vs baseline: 1.0080x; 1.0080x over previous
; __device__ __forceinline__ void phase_p2(const Params& p, int l) {
;     ...
;     if (item >= Q_HGP && item < Q_CVS) signal_done(cnt_s);
;     else if (kind == 3) signal_done(cnt_m);
;     __syncthreads();
.LBB0_347:
	s_or_b64 exec, exec, s[6:7]
	s_mov_b64 s[0:1], 0
	s_waitcnt lgkmcnt(0)
	s_barrier
